# P7: heaviest diff-attention units (heads 2,3, qb>=32) split by key range into near/far parts on two workgroups with flash-state merge; queue in size-descending order
# speedup vs baseline: 1.0249x; 1.0114x over previous
.LBB0_450:
	s_or_b64 exec, exec, s[0:1]
	v_mov_b32_e32 v0, s10
	s_waitcnt lgkmcnt(0)
	s_barrier
	ds_read_b32 v0, v0
	s_mov_b64 s[0:1], -1
	s_waitcnt lgkmcnt(0)
	v_readfirstlane_b32 s19, v0
	s_and_b32 s98, s36, 2
	s_lshl_b32 s98, s98, 4
	s_add_i32 s98, s98, 64
	s_cmp_lt_i32 s19, s98
	s_cbranch_scc0 .LBB0_482
	s_lshr_b32 s72, s36, 2
	s_and_b32 s23, s36, 3
	s_mov_b32 s100, 0
	s_sub_i32 s96, 63, s19
	s_cmp_lt_u32 s23, 2
	s_cbranch_scc1 .Lsp_dec_done
	s_cmp_lt_i32 s19, 0x50
	s_cbranch_scc1 .Lsp_dec_blk
	s_sub_i32 s96, 0x5f, s19
	s_branch .Lsp_dec_done
.Lsp_dec_blk:
	s_mul_hi_u32 s98, s19, 0xcccccccd
	s_lshr_b32 s98, s98, 2
	s_mul_i32 s99, s98, 5
	s_sub_i32 s99, s19, s99
	s_cmp_eq_u32 s99, 2
	s_cbranch_scc0 .Lsp_dec_sub
	s_sub_i32 s96, 31, s98
	s_branch .Lsp_dec_done
.Lsp_dec_sub:
	s_lshl_b32 s98, s98, 1
	s_sub_i32 s96, 63, s98
	s_cmp_gt_u32 s99, 2
	s_cselect_b32 s98, 1, 0
	s_sub_i32 s96, s96, s98
	s_mul_i32 s98, s98, 3
	s_sub_i32 s100, s99, s98
	s_add_i32 s100, s100, 1
	s_add_i32 s101, s96, 1
	s_and_b32 s101, s101, -2
.Lsp_dec_done:
	s_mov_b32 s97, s73
	s_cmp_gt_u32 s23, 1
	s_cselect_b64 s[0:1], -1, 0
	s_lshl_b64 s[20:21], s[96:97], 17
	s_lshl_b64 s[24:25], s[72:73], 23
	s_add_u32 s20, s20, s24
	s_addc_u32 s21, s21, s25
	s_lshl_b64 s[44:45], s[20:21], 1
	s_add_u32 s20, s68, s44
	s_addc_u32 s21, s69, s45
	s_lshl_b32 s22, s23, 8
	s_add_u32 s38, s20, s22
	s_addc_u32 s39, s21, 0
	s_add_u32 s20, s78, s24
	s_addc_u32 s21, s79, s25
	s_add_u32 s48, s20, s22
	s_addc_u32 s49, s21, 0
	s_add_u32 s20, s33, s24
	s_addc_u32 s21, s4, s25
	s_add_u32 s60, s20, s22
	s_addc_u32 s61, s21, 0
	s_lshl_b32 s24, s96, 7
	v_mov_b32_e32 v5, v204
	s_add_i32 s25, s24, 0xbf
	s_ashr_i32 s25, s25, 6
	s_cmp_eq_u32 s100, 1
	s_cbranch_scc0 .Lsp_par_notnear
	s_lshl_b32 s98, s101, 16
	s_add_u32 s48, s48, s98
	s_addc_u32 s49, s49, 0
	s_add_u32 s60, s60, s98
	s_addc_u32 s61, s61, 0
	s_lshl_b32 s98, s101, 6
	s_sub_i32 s24, s24, s98
	s_sub_i32 s25, s25, s101
	s_branch .Lsp_par_done
.Lsp_par_notnear:
	s_cmp_eq_u32 s100, 2
	s_cbranch_scc0 .Lsp_par_done
	s_mov_b32 s25, s101
.Lsp_par_done:
	v_readfirstlane_b32 s21, v5
	s_ashr_i32 s20, s21, 6
	s_add_i32 s80, s25, -1
	v_bfe_u32 v0, v5, 4, 2
	s_and_b32 s22, s20, 3
	s_lshl_b32 s26, s20, 3
	s_ashr_i32 s81, s80, 31
	v_or_b32_e32 v4, s26, v0
	v_lshlrev_b32_e32 v6, 5, v0
	v_bitop3_b32 v0, s26, v5, v0 bitop3:0x36
	s_lshl_b32 s30, s22, 5
	s_max_i32 s31, s25, 2
	s_lshl_b64 s[26:27], s[80:81], 16
	v_and_b32_e32 v3, 15, v5
	v_lshlrev_b32_e32 v8, 9, v4
	v_lshlrev_b32_e32 v0, 3, v0
	s_add_u32 s28, s48, s26
	v_lshlrev_b32_e32 v7, 3, v3
	v_and_or_b32 v0, v0, s11, v8
	s_addc_u32 s29, s49, s27
	v_lshlrev_b32_e32 v188, 1, v0
	v_bitop3_b32 v0, v8, v6, v7 bitop3:0xf6
	s_add_u32 s34, s60, s26
	v_lshlrev_b32_e32 v190, 1, v0
	v_or_b32_e32 v0, 4, v4
	v_bitop3_b32 v4, v4, v5, 4 bitop3:0x36
	s_addc_u32 s35, s61, s27
	s_lshl_b32 s26, s20, 11
	v_lshlrev_b32_e32 v0, 9, v0
	v_lshlrev_b32_e32 v4, 3, v4
	s_add_i32 s26, s26, 0
	v_mov_b32_e32 v189, v1
	v_and_or_b32 v4, v4, s11, v0
	s_add_i32 s27, s26, 0x4000
	v_lshl_add_u64 v[8:9], s[28:29], 0, v[188:189]
	s_mov_b32 m0, s26
	s_nop 0
	global_load_lds_dwordx4 v[8:9], off
	v_mov_b32_e32 v191, v1
	v_lshlrev_b32_e32 v192, 1, v4
	v_bitop3_b32 v0, v0, v6, v7 bitop3:0xf6
	v_lshl_add_u64 v[8:9], s[34:35], 0, v[190:191]
	s_mov_b32 m0, s27
	s_nop 0
	global_load_lds_dwordx4 v[8:9], off
	v_mov_b32_e32 v193, v1
	s_add_i32 s27, s26, 0x400
	s_add_i32 s72, s31, -2
	v_lshlrev_b32_e32 v194, 1, v0
	v_lshl_add_u64 v[8:9], s[28:29], 0, v[192:193]
	s_mov_b32 m0, s27
	s_nop 0
	global_load_lds_dwordx4 v[8:9], off
	v_mov_b32_e32 v195, v1
	s_add_i32 s27, s26, 0x4400
	s_ashr_i32 s46, s21, 8
	s_lshl_b64 s[28:29], s[72:73], 16
	v_lshl_add_u64 v[8:9], s[34:35], 0, v[194:195]
	s_add_u32 s34, s48, s28
	s_addc_u32 s35, s49, s29
	s_add_u32 s28, s60, s28
	s_mov_b32 m0, s27
	s_nop 0
	global_load_lds_dwordx4 v[8:9], off
	s_addc_u32 s29, s61, s29
	v_lshl_add_u64 v[8:9], s[34:35], 0, v[188:189]
	v_and_b32_e32 v2, 31, v5
	s_add_i32 s27, s26, 0x8000
	s_mov_b32 m0, s27
	s_nop 0
	global_load_lds_dwordx4 v[8:9], off
	v_lshl_add_u64 v[8:9], s[28:29], 0, v[190:191]
	s_add_i32 s31, s26, 0xc000
	s_mov_b32 m0, s31
	s_nop 0
	global_load_lds_dwordx4 v[8:9], off
	v_lshl_add_u64 v[8:9], s[34:35], 0, v[192:193]
	v_or_b32_e32 v226, s30, v2
	s_add_i32 s27, s26, 0x8400
	s_mov_b32 m0, s27
	s_nop 0
	global_load_lds_dwordx4 v[8:9], off
	v_lshl_add_u64 v[8:9], s[28:29], 0, v[194:195]
	v_lshlrev_b32_e32 v0, 11, v226
	s_lshl_b32 s28, s46, 6
	v_bfe_u32 v4, v5, 5, 1
	s_add_i32 s27, s26, 0xc400
	s_mov_b32 m0, s27
	s_nop 0
	global_load_lds_dwordx4 v[8:9], off
	v_lshl_add_u64 v[8:9], s[38:39], 0, v[0:1]
	s_ashr_i32 s29, s28, 31
	v_lshl_add_u64 v[8:9], s[28:29], 1, v[8:9]
	v_lshlrev_b32_e32 v0, 4, v4
	v_lshl_add_u64 v[8:9], v[8:9], 0, v[0:1]
	global_load_dwordx4 v[144:147], v[8:9], off
	global_load_dwordx4 v[148:151], v[8:9], off offset:32
	global_load_dwordx4 v[152:155], v[8:9], off offset:64
	global_load_dwordx4 v[156:159], v[8:9], off offset:96
	v_readlane_b32 s12, v253, 34
	s_waitcnt vmcnt(0)
	v_readlane_b32 s13, v253, 35
	v_and_b32_e32 v203, 63, v5
	s_or_b64 s[82:83], s[0:1], s[12:13]
	v_mov_b32_e32 v231, 0x7f61b1e6
	s_and_b64 vcc, exec, s[82:83]
	v_cmp_eq_u32_e64 s[0:1], 0, v203
	s_waitcnt vmcnt(3)
	s_waitcnt vmcnt(2)
	s_waitcnt vmcnt(1)
	s_waitcnt vmcnt(0)
	s_cbranch_vccnz .LBB0_455
	s_lshl_b32 s72, s36, 1
	s_lshl_b64 s[28:29], s[72:73], 2
	v_readlane_b32 s12, v253, 25
	v_readlane_b32 s13, v253, 26
	s_add_u32 s27, s12, s28
	s_addc_u32 s31, s13, s29
	v_and_b32_e32 v7, 0xffff0000, v144
	s_ashr_i32 s47, s46, 31
	v_lshlrev_b32_e32 v0, 16, v144
	v_mul_f32_e32 v7, v7, v7
	s_lshl_b64 s[28:29], s[46:47], 2
	v_fmac_f32_e32 v7, v0, v0
	v_lshlrev_b32_e32 v0, 16, v145
	s_add_u32 s28, s27, s28
	v_fmac_f32_e32 v7, v0, v0
	v_and_b32_e32 v0, 0xffff0000, v145
	s_addc_u32 s29, s31, s29
	v_fmac_f32_e32 v7, v0, v0
	global_load_dword v0, v1, s[28:29]
	v_lshlrev_b32_e32 v8, 16, v146
	v_fmac_f32_e32 v7, v8, v8
	v_and_b32_e32 v8, 0xffff0000, v146
	v_fmac_f32_e32 v7, v8, v8
	v_lshlrev_b32_e32 v8, 16, v147
	v_fmac_f32_e32 v7, v8, v8
	v_and_b32_e32 v8, 0xffff0000, v147
	v_fmac_f32_e32 v7, v8, v8
	v_lshlrev_b32_e32 v8, 16, v148
	v_fmac_f32_e32 v7, v8, v8
	v_and_b32_e32 v8, 0xffff0000, v148
	v_fmac_f32_e32 v7, v8, v8
	v_lshlrev_b32_e32 v8, 16, v149
	v_fmac_f32_e32 v7, v8, v8
	v_and_b32_e32 v8, 0xffff0000, v149
	v_fmac_f32_e32 v7, v8, v8
	v_lshlrev_b32_e32 v8, 16, v150
	v_fmac_f32_e32 v7, v8, v8
	v_and_b32_e32 v8, 0xffff0000, v150
	v_fmac_f32_e32 v7, v8, v8
	v_lshlrev_b32_e32 v8, 16, v151
	v_fmac_f32_e32 v7, v8, v8
	v_and_b32_e32 v8, 0xffff0000, v151
	v_fmac_f32_e32 v7, v8, v8
	v_lshlrev_b32_e32 v8, 16, v152
	v_fmac_f32_e32 v7, v8, v8
	v_and_b32_e32 v8, 0xffff0000, v152
	v_fmac_f32_e32 v7, v8, v8
	v_lshlrev_b32_e32 v8, 16, v153
	v_fmac_f32_e32 v7, v8, v8
	v_and_b32_e32 v8, 0xffff0000, v153
	v_fmac_f32_e32 v7, v8, v8
	v_lshlrev_b32_e32 v8, 16, v154
	v_fmac_f32_e32 v7, v8, v8
	v_and_b32_e32 v8, 0xffff0000, v154
	v_fmac_f32_e32 v7, v8, v8
	v_lshlrev_b32_e32 v8, 16, v155
	v_fmac_f32_e32 v7, v8, v8
	v_and_b32_e32 v8, 0xffff0000, v155
	v_fmac_f32_e32 v7, v8, v8
	v_and_b32_e32 v9, 0xffff0000, v156
	v_lshlrev_b32_e32 v8, 16, v156
	v_pk_mul_f32 v[8:9], v[8:9], v[8:9]
	s_mov_b32 s12, 0xf800000
	v_add_f32_e32 v7, v8, v7
	v_add_f32_e32 v7, v9, v7
	v_and_b32_e32 v9, 0xffff0000, v157
	v_lshlrev_b32_e32 v8, 16, v157
	v_pk_mul_f32 v[8:9], v[8:9], v[8:9]
	s_nop 0
	v_add_f32_e32 v7, v8, v7
	v_add_f32_e32 v7, v9, v7
	v_and_b32_e32 v9, 0xffff0000, v158
	v_lshlrev_b32_e32 v8, 16, v158
	v_pk_mul_f32 v[8:9], v[8:9], v[8:9]
	s_nop 0
	v_add_f32_e32 v7, v8, v7
	v_add_f32_e32 v7, v9, v7
	v_and_b32_e32 v9, 0xffff0000, v159
	v_lshlrev_b32_e32 v8, 16, v159
	v_pk_mul_f32 v[8:9], v[8:9], v[8:9]
	s_nop 0
	v_add_f32_e32 v7, v8, v7
	v_add_f32_e32 v7, v9, v7
	ds_bpermute_b32 v8, v225, v7
	s_waitcnt lgkmcnt(0)
	v_add_f32_e32 v7, v7, v8
	v_mul_f32_e32 v8, 0x4f800000, v7
	v_cmp_gt_f32_e32 vcc, s12, v7
	s_nop 1
	v_cndmask_b32_e32 v7, v7, v8, vcc
	v_sqrt_f32_e32 v8, v7
	s_nop 0
	v_add_u32_e32 v9, -1, v8
	v_fma_f32 v10, -v9, v8, v7
	v_cmp_ge_f32_e64 s[38:39], 0, v10
	v_add_u32_e32 v10, 1, v8
	v_fma_f32 v11, -v10, v8, v7
	v_cmp_lt_f32_e64 s[42:43], 0, v11
	s_and_saveexec_b64 s[84:85], s[0:1]
	s_cbranch_execz .LBB0_454
	s_lshl_b32 s0, s20, 2
	s_add_i32 s0, s0, 0
	s_add_i32 s0, s0, 0x20040
	v_mov_b32_e32 v11, s0
	ds_write_b32 v11, v1
	ds_write_b32 v11, v1 offset:32

.LBB0_455:
	v_lshrrev_b32_e32 v0, 2, v3
	v_lshlrev_b32_e32 v7, 10, v4
	v_lshlrev_b32_e32 v8, 8, v0
	v_and_b32_e32 v6, 32, v6
	v_lshlrev_b32_e32 v5, 3, v5
	v_or3_b32 v6, v7, v8, v6
	v_and_b32_e32 v5, 24, v5
	v_lshlrev_b32_e32 v0, 6, v0
	v_or3_b32 v0, v6, v5, v0
	s_movk_i32 s0, 0x80
	v_bitop3_b32 v229, v0, s0, v217 bitop3:0x36
	s_movk_i32 s0, 0xc0
	s_cmp_gt_i32 s20, 3
	v_lshlrev_b32_e32 v202, 2, v4
	v_or_b32_e32 v227, 0x4000, v0
	v_bitop3_b32 v228, v0, 64, v217 bitop3:0x36
	v_bitop3_b32 v230, v0, s0, v217 bitop3:0x36
	s_mov_b64 s[84:85], -1
	s_cmp_lt_i32 s25, 1
	s_mov_b32 s27, 0
	s_cbranch_scc1 .LBB0_498
	s_not_b32 s1, s23
	s_lshl_b32 s1, s1, 1
	v_ldexp_f32 v0, 1.0, s1
	v_or_b32_e32 v198, s24, v226
	v_mul_f32_e32 v196, 0x3fb8aa3b, v0
	v_sub_u32_e32 v0, v202, v198
	v_add_u32_e32 v5, 1, v0
	v_cvt_f32_i32_e32 v6, v0
	v_cvt_f32_i32_e32 v7, v5
	v_add_u32_e32 v5, 2, v0
	v_add_u32_e32 v8, 3, v0
	v_cvt_f32_i32_e32 v9, v8
	v_cvt_f32_i32_e32 v8, v5
	v_add_u32_e32 v5, 8, v0
	v_add_u32_e32 v10, 9, v0
	v_cvt_f32_i32_e32 v11, v10
	v_cvt_f32_i32_e32 v10, v5
	v_mov_b32_e32 v197, v196
	v_add_u32_e32 v5, 10, v0
	v_add_u32_e32 v12, 11, v0
	v_cvt_f32_i32_e32 v13, v12
	v_cvt_f32_i32_e32 v12, v5
	v_pk_mul_f32 v[80:81], v[196:197], v[6:7] op_sel_hi:[0,1]
	v_add_u32_e32 v5, 16, v0
	v_add_u32_e32 v6, 17, v0
	v_pk_mul_f32 v[82:83], v[196:197], v[8:9] op_sel_hi:[0,1]
	v_cvt_f32_i32_e32 v7, v6
	v_cvt_f32_i32_e32 v6, v5
	v_add_u32_e32 v5, 18, v0
	v_add_u32_e32 v8, 19, v0
	v_pk_mul_f32 v[84:85], v[196:197], v[10:11] op_sel_hi:[0,1]
	v_cvt_f32_i32_e32 v9, v8
	v_cvt_f32_i32_e32 v8, v5
	v_add_u32_e32 v5, 24, v0
	v_add_u32_e32 v10, 25, v0
	v_cvt_f32_i32_e32 v11, v10
	v_cvt_f32_i32_e32 v10, v5
	v_pk_mul_f32 v[86:87], v[196:197], v[12:13] op_sel_hi:[0,1]
	v_add_u32_e32 v5, 26, v0
	v_add_u32_e32 v12, 27, v0
	v_cvt_f32_i32_e32 v13, v12
	v_cvt_f32_i32_e32 v12, v5
	v_pk_mul_f32 v[88:89], v[196:197], v[6:7] op_sel_hi:[0,1]
	v_add_u32_e32 v5, 32, v0
	v_add_u32_e32 v6, 33, v0
	v_pk_mul_f32 v[90:91], v[196:197], v[8:9] op_sel_hi:[0,1]
	v_cvt_f32_i32_e32 v7, v6
	v_cvt_f32_i32_e32 v6, v5
	v_add_u32_e32 v5, 34, v0
	v_add_u32_e32 v8, 35, v0
	v_pk_mul_f32 v[92:93], v[196:197], v[10:11] op_sel_hi:[0,1]
	v_cvt_f32_i32_e32 v9, v8
	v_cvt_f32_i32_e32 v8, v5
	v_add_u32_e32 v5, 40, v0
	v_add_u32_e32 v10, 41, v0
	v_cvt_f32_i32_e32 v11, v10
	v_cvt_f32_i32_e32 v10, v5
	v_pk_mul_f32 v[94:95], v[196:197], v[12:13] op_sel_hi:[0,1]
	v_add_u32_e32 v5, 42, v0
	v_add_u32_e32 v12, 43, v0
	v_cvt_f32_i32_e32 v13, v12
	v_cvt_f32_i32_e32 v12, v5
	v_pk_mul_f32 v[96:97], v[196:197], v[6:7] op_sel_hi:[0,1]
	v_add_u32_e32 v5, 48, v0
	v_add_u32_e32 v6, 49, v0
	s_lshl_b32 s0, s20, 2
	v_pk_mul_f32 v[98:99], v[196:197], v[8:9] op_sel_hi:[0,1]
	v_cvt_f32_i32_e32 v7, v6
	v_cvt_f32_i32_e32 v6, v5
	v_add_u32_e32 v5, 50, v0
	v_add_u32_e32 v8, 51, v0
	s_add_i32 s28, s0, 0
	s_lshl_b32 s0, s96, 1
	s_lshr_b32 s1, s22, 1
	v_pk_mul_f32 v[100:101], v[196:197], v[10:11] op_sel_hi:[0,1]
	v_cvt_f32_i32_e32 v9, v8
	v_cvt_f32_i32_e32 v8, v5
	v_add_u32_e32 v5, 56, v0
	v_add_u32_e32 v10, 57, v0
	s_or_b32 s37, s1, s0
	s_cmp_eq_u32 s100, 1
	s_cselect_b32 s98, s101, 0
	s_sub_i32 s37, s37, s98
	s_lshr_b32 s98, s36, 2
	s_lshl_b32 s98, s98, 6
	s_and_b32 s99, s36, 3
	s_lshl_b32 s99, s99, 5
	s_add_i32 s98, s98, s99
	s_add_i32 s98, s98, s96
	s_add_i32 s101, s98, 0xffffffa0
	v_cvt_f32_i32_e32 v11, v10
	v_cvt_f32_i32_e32 v10, v5
	v_add_u32_e32 v5, 58, v0
	v_add_u32_e32 v0, 59, v0
	s_lshl_b32 s0, s46, 3
	v_pk_mul_f32 v[102:103], v[196:197], v[12:13] op_sel_hi:[0,1]
	v_cvt_f32_i32_e32 v13, v0
	v_cvt_f32_i32_e32 v12, v5
	v_lshlrev_b32_e32 v0, 8, v2
	v_or_b32_e32 v5, s0, v4
	v_bitop3_b32 v4, s0, v3, v4 bitop3:0x36
	v_lshl_add_u32 v233, v4, 4, v0
	v_bitop3_b32 v4, v5, v3, 2 bitop3:0x36
	v_lshl_add_u32 v234, v4, 4, v0
	v_bitop3_b32 v4, v5, v3, 4 bitop3:0x36
	v_bitop3_b32 v3, v5, v3, 6 bitop3:0x36
	s_addk_i32 s30, 0x1fc1
	v_lshl_add_u32 v235, v4, 4, v0
	v_lshl_add_u32 v236, v3, 4, v0
	s_lshl_b32 s31, s25, 6
	v_add_u32_e32 v0, s30, v2
	v_subrev_u32_e32 v0, s31, v0
	s_lshl_b32 s19, s19, 7
	v_mov_b32_e32 v14, v1
	v_mov_b32_e32 v15, v1
	v_mov_b32_e32 v172, v1
	v_mov_b32_e32 v173, v1
	s_add_i32 s29, s24, 0x80
	v_pk_mul_f32 v[104:105], v[196:197], v[6:7] op_sel_hi:[0,1]
	v_pk_mul_f32 v[106:107], v[196:197], v[8:9] op_sel_hi:[0,1]
	v_pk_mul_f32 v[108:109], v[196:197], v[10:11] op_sel_hi:[0,1]
	v_pk_mul_f32 v[110:111], v[196:197], v[12:13] op_sel_hi:[0,1]
	s_lshl_b32 s34, s25, 3
	v_subrev_u32_e32 v237, s19, v0
	s_lshl_b32 s19, s25, 5
	v_mov_b32_e32 v0, v1
	v_mov_b32_e32 v2, v1
	v_mov_b32_e32 v3, v1
	v_mov_b32_e32 v4, v1
	v_mov_b32_e32 v5, v1
	v_mov_b32_e32 v6, v1
	v_mov_b32_e32 v7, v1
	v_mov_b32_e32 v8, v1
	v_mov_b32_e32 v9, v1
	v_mov_b32_e32 v10, v1
	v_mov_b32_e32 v11, v1
	v_mov_b32_e32 v12, v1
	v_mov_b32_e32 v13, v1
	v_mov_b32_e32 v174, v1
	v_mov_b32_e32 v175, v1
	v_mov_b64_e32 v[168:169], v[172:173]
	v_mov_b64_e32 v[164:165], v[172:173]
	v_mov_b64_e32 v[160:161], v[172:173]
	v_mov_b64_e32 v[78:79], v[14:15]
	v_mov_b64_e32 v[62:63], v[14:15]
	v_mov_b64_e32 v[46:47], v[14:15]
	v_mov_b64_e32 v[30:31], v[14:15]
	s_xor_b64 s[88:89], s[82:83], -1
	s_add_i32 s28, s28, 0x20040
	v_cmp_eq_u32_e64 s[0:1], 0, v203
	s_mov_b32 s47, s29
	v_mov_b32_e32 v199, v198
	s_sub_i32 s67, s31, 64
	s_add_i32 s72, s34, -16
	s_sub_i32 s81, s19, 32
	s_mov_b64 s[96:97], 0
	v_mov_b32_e32 v201, 0xf149f2ca
	v_mov_b32_e32 v232, 0
	v_mov_b64_e32 v[170:171], v[174:175]
	v_mov_b64_e32 v[166:167], v[174:175]
	v_mov_b64_e32 v[162:163], v[174:175]
	v_mov_b64_e32 v[76:77], v[12:13]
	v_mov_b64_e32 v[74:75], v[10:11]
	v_mov_b64_e32 v[72:73], v[8:9]
	v_mov_b64_e32 v[70:71], v[6:7]
	v_mov_b64_e32 v[68:69], v[4:5]
	v_mov_b64_e32 v[66:67], v[2:3]
	v_mov_b64_e32 v[64:65], v[0:1]
	v_mov_b64_e32 v[60:61], v[12:13]
	v_mov_b64_e32 v[58:59], v[10:11]
	v_mov_b64_e32 v[56:57], v[8:9]
	v_mov_b64_e32 v[54:55], v[6:7]
	v_mov_b64_e32 v[52:53], v[4:5]
	v_mov_b64_e32 v[50:51], v[2:3]
	v_mov_b64_e32 v[48:49], v[0:1]
	v_mov_b64_e32 v[44:45], v[12:13]
	v_mov_b64_e32 v[42:43], v[10:11]
	v_mov_b64_e32 v[40:41], v[8:9]
	v_mov_b64_e32 v[38:39], v[6:7]
	v_mov_b64_e32 v[36:37], v[4:5]
	v_mov_b64_e32 v[34:35], v[2:3]
	v_mov_b64_e32 v[32:33], v[0:1]
	v_mov_b64_e32 v[28:29], v[12:13]
	v_mov_b64_e32 v[26:27], v[10:11]
	v_mov_b64_e32 v[24:25], v[8:9]
	v_mov_b64_e32 v[22:23], v[6:7]
	v_mov_b64_e32 v[20:21], v[4:5]
	v_mov_b64_e32 v[18:19], v[2:3]
	v_mov_b64_e32 v[16:17], v[0:1]
	s_mov_b32 s50, 0
	s_branch .LBB0_458

.LBB0_485:
	s_or_b64 exec, exec, s[0:1]
	s_add_i32 s0, s36, 1
	s_and_b32 s0, s0, 7
	s_lshl_b32 s1, s0, 2
	s_add_i32 s1, s1, 0
	s_add_i32 s1, s1, 0x20010
	v_mov_b32_e32 v0, s1
	s_waitcnt lgkmcnt(0)
	s_barrier
	ds_read_b32 v0, v0
	s_waitcnt lgkmcnt(0)
	s_and_b32 s99, s0, 2
	s_lshl_b32 s99, s99, 4
	s_add_i32 s99, s99, 64
	v_cmp_gt_u32_e32 vcc, s99, v0
	s_cbranch_vccnz .LBB0_492
	s_add_i32 s0, s36, 2
	s_and_b32 s0, s0, 7
	s_lshl_b32 s1, s0, 2
	s_add_i32 s1, s1, 0
	s_add_i32 s1, s1, 0x20010
	v_mov_b32_e32 v0, s1
	ds_read_b32 v0, v0
	s_waitcnt lgkmcnt(0)
	v_readfirstlane_b32 s1, v0
	s_and_b32 s99, s0, 2
	s_lshl_b32 s99, s99, 4
	s_add_i32 s99, s99, 64
	s_cmp_lt_u32 s1, s99
	s_cselect_b32 s0, s0, -1
	s_cmp_gt_i32 s0, -1
	s_cbranch_scc1 .LBB0_493
.LBB0_487:
	s_add_i32 s0, s36, 3
	s_and_b32 s0, s0, 7
	s_lshl_b32 s1, s0, 2
	s_add_i32 s1, s1, 0
	s_add_i32 s1, s1, 0x20010
	v_mov_b32_e32 v0, s1
	ds_read_b32 v0, v0
	s_waitcnt lgkmcnt(0)
	v_readfirstlane_b32 s1, v0
	s_and_b32 s99, s0, 2
	s_lshl_b32 s99, s99, 4
	s_add_i32 s99, s99, 64
	s_cmp_lt_u32 s1, s99
	s_cselect_b32 s0, s0, -1
	s_cmp_gt_i32 s0, -1
	s_cbranch_scc1 .LBB0_494
.LBB0_488:
	s_and_b32 s0, s36, 7
	s_xor_b32 s0, s0, 4
	s_lshl_b32 s1, s0, 2
	s_add_i32 s1, s1, 0
	s_add_i32 s1, s1, 0x20010
	v_mov_b32_e32 v0, s1
	ds_read_b32 v0, v0
	s_waitcnt lgkmcnt(0)
	v_readfirstlane_b32 s1, v0
	s_and_b32 s99, s0, 2
	s_lshl_b32 s99, s99, 4
	s_add_i32 s99, s99, 64
	s_cmp_lt_u32 s1, s99
	s_cselect_b32 s0, s0, -1
	s_cmp_gt_i32 s0, -1
	s_cbranch_scc1 .LBB0_495
.LBB0_489:
	s_add_i32 s0, s36, 5
	s_and_b32 s0, s0, 7
	s_lshl_b32 s1, s0, 2
	s_add_i32 s1, s1, 0
	s_add_i32 s1, s1, 0x20010
	v_mov_b32_e32 v0, s1
	ds_read_b32 v0, v0
	s_waitcnt lgkmcnt(0)
	v_readfirstlane_b32 s1, v0
	s_and_b32 s99, s0, 2
	s_lshl_b32 s99, s99, 4
	s_add_i32 s99, s99, 64
	s_cmp_lt_u32 s1, s99
	s_cselect_b32 s0, s0, -1
	s_cmp_gt_i32 s0, -1
	s_cbranch_scc1 .LBB0_496
.LBB0_490:
	s_add_i32 s0, s36, 6
	s_and_b32 s0, s0, 7
	s_lshl_b32 s1, s0, 2
	s_add_i32 s1, s1, 0
	s_add_i32 s1, s1, 0x20010
	v_mov_b32_e32 v0, s1
	ds_read_b32 v0, v0
	s_waitcnt lgkmcnt(0)
	v_readfirstlane_b32 s1, v0
	s_and_b32 s99, s0, 2
	s_lshl_b32 s99, s99, 4
	s_add_i32 s99, s99, 64
	s_cmp_lt_u32 s1, s99
	s_cselect_b32 s0, s0, -1
	s_cmp_gt_i32 s0, -1
	s_cbranch_scc1 .LBB0_497
.LBB0_491:
	s_add_i32 s0, s36, -1
	s_and_b32 s0, s0, 7
	s_lshl_b32 s1, s0, 2
	s_add_i32 s1, s1, 0
	s_add_i32 s1, s1, 0x20010
	v_mov_b32_e32 v0, s1
	ds_read_b32 v0, v0
	s_waitcnt lgkmcnt(0)
	v_readfirstlane_b32 s1, v0
	s_and_b32 s99, s0, 2
	s_lshl_b32 s99, s99, 4
	s_add_i32 s99, s99, 64
	s_cmp_lt_u32 s1, s99
	s_cselect_b32 s0, s0, -1
	s_branch .LBB0_497

.LBB0_501:
	s_cmp_eq_u32 s100, 0
	s_cbranch_scc1 .Lsp_epi
	s_nop 15
	s_nop 3
	v_readlane_b32 s12, v253, 2
	v_readlane_b32 s13, v253, 3
	s_waitcnt vmcnt(0) lgkmcnt(0)
	s_barrier
	s_lshl_b32 s98, s101, 2
	s_add_u32 s98, s54, s98
	s_addc_u32 s99, s55, 0
	s_and_saveexec_b64 s[34:35], s[12:13]
	s_cbranch_execz .Lsp_a1
	v_mov_b32_e32 v2, 0xca000
	v_mov_b32_e32 v3, 1
	global_atomic_add v3, v2, v3, s[98:99] sc0
	s_waitcnt vmcnt(0)
	v_mov_b32_e32 v2, 0x2000c
	ds_write_b32 v2, v3
	s_waitcnt lgkmcnt(0)
.Lsp_a1:
	s_or_b64 exec, exec, s[34:35]
	s_barrier
	v_mov_b32_e32 v2, 0x2000c
	ds_read_b32 v2, v2
	s_waitcnt lgkmcnt(0)
	v_readfirstlane_b32 s19, v2
	s_mul_i32 s42, s101, 0x22000
	s_add_u32 s42, s42, 0x2c00000
	s_add_u32 s42, s52, s42
	s_addc_u32 s43, s53, 0
	v_lshlrev_b32_e32 v2, 4, v204
	s_cmp_eq_u32 s19, 0
	s_cbranch_scc0 .Lsp_second
	global_store_dwordx4 v2, v[16:19], s[42:43]
	s_add_u32 s42, s42, 0x2000
	s_addc_u32 s43, s43, 0
	global_store_dwordx4 v2, v[20:23], s[42:43]
	s_add_u32 s42, s42, 0x2000
	s_addc_u32 s43, s43, 0
	global_store_dwordx4 v2, v[24:27], s[42:43]
	s_add_u32 s42, s42, 0x2000
	s_addc_u32 s43, s43, 0
	global_store_dwordx4 v2, v[28:31], s[42:43]
	s_add_u32 s42, s42, 0x2000
	s_addc_u32 s43, s43, 0
	global_store_dwordx4 v2, v[32:35], s[42:43]
	s_add_u32 s42, s42, 0x2000
	s_addc_u32 s43, s43, 0
	global_store_dwordx4 v2, v[36:39], s[42:43]
	s_add_u32 s42, s42, 0x2000
	s_addc_u32 s43, s43, 0
	global_store_dwordx4 v2, v[40:43], s[42:43]
	s_add_u32 s42, s42, 0x2000
	s_addc_u32 s43, s43, 0
	global_store_dwordx4 v2, v[44:47], s[42:43]
	s_add_u32 s42, s42, 0x2000
	s_addc_u32 s43, s43, 0
	global_store_dwordx4 v2, v[48:51], s[42:43]
	s_add_u32 s42, s42, 0x2000
	s_addc_u32 s43, s43, 0
	global_store_dwordx4 v2, v[52:55], s[42:43]
	s_add_u32 s42, s42, 0x2000
	s_addc_u32 s43, s43, 0
	global_store_dwordx4 v2, v[56:59], s[42:43]
	s_add_u32 s42, s42, 0x2000
	s_addc_u32 s43, s43, 0
	global_store_dwordx4 v2, v[60:63], s[42:43]
	s_add_u32 s42, s42, 0x2000
	s_addc_u32 s43, s43, 0
	global_store_dwordx4 v2, v[64:67], s[42:43]
	s_add_u32 s42, s42, 0x2000
	s_addc_u32 s43, s43, 0
	global_store_dwordx4 v2, v[68:71], s[42:43]
	s_add_u32 s42, s42, 0x2000
	s_addc_u32 s43, s43, 0
	global_store_dwordx4 v2, v[72:75], s[42:43]
	s_add_u32 s42, s42, 0x2000
	s_addc_u32 s43, s43, 0
	global_store_dwordx4 v2, v[76:79], s[42:43]
	s_add_u32 s42, s42, 0x2000
	s_addc_u32 s43, s43, 0
	v_mov_b32_e32 v4, v201
	v_mov_b32_e32 v5, v232
	global_store_dwordx2 v2, v[4:5], s[42:43]
	s_waitcnt vmcnt(0)
	s_barrier
	s_and_saveexec_b64 s[34:35], s[12:13]
	s_cbranch_execz .Lsp_f1
	buffer_wbl2 sc1
	s_waitcnt vmcnt(0)
	v_mov_b32_e32 v2, 0xca800
	v_mov_b32_e32 v3, 1
	global_atomic_add v2, v3, s[98:99]
	s_waitcnt vmcnt(0)
.Lsp_f1:
	s_or_b64 exec, exec, s[34:35]
	s_branch .LBB0_505
.Lsp_second:
	s_and_saveexec_b64 s[34:35], s[12:13]
	s_cbranch_execz .Lsp_s1
	s_mov_b32 s19, 0
	v_mov_b32_e32 v3, 0xca800
.Lsp_spin:
	global_load_dword v4, v3, s[98:99] sc1
	s_waitcnt vmcnt(0)
	v_cmp_ne_u32_e32 vcc, 0, v4
	s_cbranch_vccnz .Lsp_spun
	s_sleep 2
	s_add_i32 s19, s19, 1
	s_cmp_lt_u32 s19, 0x4000
	s_cbranch_scc1 .Lsp_spin
.Lsp_spun:
	buffer_inv sc1
	s_waitcnt vmcnt(0)
.Lsp_s1:
	s_or_b64 exec, exec, s[34:35]
	s_barrier
	s_add_u32 s98, s42, 0x20000
	s_addc_u32 s99, s43, 0
	global_load_dwordx2 v[4:5], v2, s[98:99]
	s_waitcnt vmcnt(0)
	v_max_f32_e32 v6, v201, v201
	v_max_f32_e32 v7, v4, v4
	v_max_f32_e32 v6, v6, v7
	v_sub_f32_e32 v7, v201, v6
	v_sub_f32_e32 v8, v4, v6
	v_exp_f32_e32 v7, v7
	v_exp_f32_e32 v8, v8
	v_mov_b32_e32 v201, v6
	v_mul_f32_e32 v232, v232, v7
	v_fmac_f32_e32 v232, v5, v8
	global_load_dwordx4 v[80:83], v2, s[42:43]
	s_add_u32 s42, s42, 0x2000
	s_addc_u32 s43, s43, 0
	global_load_dwordx4 v[84:87], v2, s[42:43]
	s_add_u32 s42, s42, 0x2000
	s_addc_u32 s43, s43, 0
	global_load_dwordx4 v[88:91], v2, s[42:43]
	s_add_u32 s42, s42, 0x2000
	s_addc_u32 s43, s43, 0
	global_load_dwordx4 v[92:95], v2, s[42:43]
	s_add_u32 s42, s42, 0x2000
	s_addc_u32 s43, s43, 0
	s_waitcnt vmcnt(0)
	v_mul_f32_e32 v16, v16, v7
	v_fmac_f32_e32 v16, v80, v8
	v_mul_f32_e32 v17, v17, v7
	v_fmac_f32_e32 v17, v81, v8
	v_mul_f32_e32 v18, v18, v7
	v_fmac_f32_e32 v18, v82, v8
	v_mul_f32_e32 v19, v19, v7
	v_fmac_f32_e32 v19, v83, v8
	v_mul_f32_e32 v20, v20, v7
	v_fmac_f32_e32 v20, v84, v8
	v_mul_f32_e32 v21, v21, v7
	v_fmac_f32_e32 v21, v85, v8
	v_mul_f32_e32 v22, v22, v7
	v_fmac_f32_e32 v22, v86, v8
	v_mul_f32_e32 v23, v23, v7
	v_fmac_f32_e32 v23, v87, v8
	v_mul_f32_e32 v24, v24, v7
	v_fmac_f32_e32 v24, v88, v8
	v_mul_f32_e32 v25, v25, v7
	v_fmac_f32_e32 v25, v89, v8
	v_mul_f32_e32 v26, v26, v7
	v_fmac_f32_e32 v26, v90, v8
	v_mul_f32_e32 v27, v27, v7
	v_fmac_f32_e32 v27, v91, v8
	v_mul_f32_e32 v28, v28, v7
	v_fmac_f32_e32 v28, v92, v8
	v_mul_f32_e32 v29, v29, v7
	v_fmac_f32_e32 v29, v93, v8
	v_mul_f32_e32 v30, v30, v7
	v_fmac_f32_e32 v30, v94, v8
	v_mul_f32_e32 v31, v31, v7
	v_fmac_f32_e32 v31, v95, v8
	global_load_dwordx4 v[80:83], v2, s[42:43]
	s_add_u32 s42, s42, 0x2000
	s_addc_u32 s43, s43, 0
	global_load_dwordx4 v[84:87], v2, s[42:43]
	s_add_u32 s42, s42, 0x2000
	s_addc_u32 s43, s43, 0
	global_load_dwordx4 v[88:91], v2, s[42:43]
	s_add_u32 s42, s42, 0x2000
	s_addc_u32 s43, s43, 0
	global_load_dwordx4 v[92:95], v2, s[42:43]
	s_add_u32 s42, s42, 0x2000
	s_addc_u32 s43, s43, 0
	s_waitcnt vmcnt(0)
	v_mul_f32_e32 v32, v32, v7
	v_fmac_f32_e32 v32, v80, v8
	v_mul_f32_e32 v33, v33, v7
	v_fmac_f32_e32 v33, v81, v8
	v_mul_f32_e32 v34, v34, v7
	v_fmac_f32_e32 v34, v82, v8
	v_mul_f32_e32 v35, v35, v7
	v_fmac_f32_e32 v35, v83, v8
	v_mul_f32_e32 v36, v36, v7
	v_fmac_f32_e32 v36, v84, v8
	v_mul_f32_e32 v37, v37, v7
	v_fmac_f32_e32 v37, v85, v8
	v_mul_f32_e32 v38, v38, v7
	v_fmac_f32_e32 v38, v86, v8
	v_mul_f32_e32 v39, v39, v7
	v_fmac_f32_e32 v39, v87, v8
	v_mul_f32_e32 v40, v40, v7
	v_fmac_f32_e32 v40, v88, v8
	v_mul_f32_e32 v41, v41, v7
	v_fmac_f32_e32 v41, v89, v8
	v_mul_f32_e32 v42, v42, v7
	v_fmac_f32_e32 v42, v90, v8
	v_mul_f32_e32 v43, v43, v7
	v_fmac_f32_e32 v43, v91, v8
	v_mul_f32_e32 v44, v44, v7
	v_fmac_f32_e32 v44, v92, v8
	v_mul_f32_e32 v45, v45, v7
	v_fmac_f32_e32 v45, v93, v8
	v_mul_f32_e32 v46, v46, v7
	v_fmac_f32_e32 v46, v94, v8
	v_mul_f32_e32 v47, v47, v7
	v_fmac_f32_e32 v47, v95, v8
	global_load_dwordx4 v[80:83], v2, s[42:43]
	s_add_u32 s42, s42, 0x2000
	s_addc_u32 s43, s43, 0
	global_load_dwordx4 v[84:87], v2, s[42:43]
	s_add_u32 s42, s42, 0x2000
	s_addc_u32 s43, s43, 0
	global_load_dwordx4 v[88:91], v2, s[42:43]
	s_add_u32 s42, s42, 0x2000
	s_addc_u32 s43, s43, 0
	global_load_dwordx4 v[92:95], v2, s[42:43]
	s_add_u32 s42, s42, 0x2000
	s_addc_u32 s43, s43, 0
	s_waitcnt vmcnt(0)
	v_mul_f32_e32 v48, v48, v7
	v_fmac_f32_e32 v48, v80, v8
	v_mul_f32_e32 v49, v49, v7
	v_fmac_f32_e32 v49, v81, v8
	v_mul_f32_e32 v50, v50, v7
	v_fmac_f32_e32 v50, v82, v8
	v_mul_f32_e32 v51, v51, v7
	v_fmac_f32_e32 v51, v83, v8
	v_mul_f32_e32 v52, v52, v7
	v_fmac_f32_e32 v52, v84, v8
	v_mul_f32_e32 v53, v53, v7
	v_fmac_f32_e32 v53, v85, v8
	v_mul_f32_e32 v54, v54, v7
	v_fmac_f32_e32 v54, v86, v8
	v_mul_f32_e32 v55, v55, v7
	v_fmac_f32_e32 v55, v87, v8
	v_mul_f32_e32 v56, v56, v7
	v_fmac_f32_e32 v56, v88, v8
	v_mul_f32_e32 v57, v57, v7
	v_fmac_f32_e32 v57, v89, v8
	v_mul_f32_e32 v58, v58, v7
	v_fmac_f32_e32 v58, v90, v8
	v_mul_f32_e32 v59, v59, v7
	v_fmac_f32_e32 v59, v91, v8
	v_mul_f32_e32 v60, v60, v7
	v_fmac_f32_e32 v60, v92, v8
	v_mul_f32_e32 v61, v61, v7
	v_fmac_f32_e32 v61, v93, v8
	v_mul_f32_e32 v62, v62, v7
	v_fmac_f32_e32 v62, v94, v8
	v_mul_f32_e32 v63, v63, v7
	v_fmac_f32_e32 v63, v95, v8
	global_load_dwordx4 v[80:83], v2, s[42:43]
	s_add_u32 s42, s42, 0x2000
	s_addc_u32 s43, s43, 0
	global_load_dwordx4 v[84:87], v2, s[42:43]
	s_add_u32 s42, s42, 0x2000
	s_addc_u32 s43, s43, 0
	global_load_dwordx4 v[88:91], v2, s[42:43]
	s_add_u32 s42, s42, 0x2000
	s_addc_u32 s43, s43, 0
	global_load_dwordx4 v[92:95], v2, s[42:43]
	s_add_u32 s42, s42, 0x2000
	s_addc_u32 s43, s43, 0
	s_waitcnt vmcnt(0)
	v_mul_f32_e32 v64, v64, v7
	v_fmac_f32_e32 v64, v80, v8
	v_mul_f32_e32 v65, v65, v7
	v_fmac_f32_e32 v65, v81, v8
	v_mul_f32_e32 v66, v66, v7
	v_fmac_f32_e32 v66, v82, v8
	v_mul_f32_e32 v67, v67, v7
	v_fmac_f32_e32 v67, v83, v8
	v_mul_f32_e32 v68, v68, v7
	v_fmac_f32_e32 v68, v84, v8
	v_mul_f32_e32 v69, v69, v7
	v_fmac_f32_e32 v69, v85, v8
	v_mul_f32_e32 v70, v70, v7
	v_fmac_f32_e32 v70, v86, v8
	v_mul_f32_e32 v71, v71, v7
	v_fmac_f32_e32 v71, v87, v8
	v_mul_f32_e32 v72, v72, v7
	v_fmac_f32_e32 v72, v88, v8
	v_mul_f32_e32 v73, v73, v7
	v_fmac_f32_e32 v73, v89, v8
	v_mul_f32_e32 v74, v74, v7
	v_fmac_f32_e32 v74, v90, v8
	v_mul_f32_e32 v75, v75, v7
	v_fmac_f32_e32 v75, v91, v8
	v_mul_f32_e32 v76, v76, v7
	v_fmac_f32_e32 v76, v92, v8
	v_mul_f32_e32 v77, v77, v7
	v_fmac_f32_e32 v77, v93, v8
	v_mul_f32_e32 v78, v78, v7
	v_fmac_f32_e32 v78, v94, v8
	v_mul_f32_e32 v79, v79, v7
	v_fmac_f32_e32 v79, v95, v8

	.amdhsa_kernel _Z8yoco_fwd6Params
		.amdhsa_group_segment_fixed_size 0
		.amdhsa_private_segment_fixed_size 0
		.amdhsa_kernarg_size 464
		.amdhsa_user_sgpr_count 2
		.amdhsa_user_sgpr_dispatch_ptr 0
		.amdhsa_user_sgpr_queue_ptr 0
		.amdhsa_user_sgpr_kernarg_segment_ptr 1
		.amdhsa_user_sgpr_dispatch_id 0
		.amdhsa_user_sgpr_kernarg_preload_length 0
		.amdhsa_user_sgpr_kernarg_preload_offset 0
		.amdhsa_user_sgpr_private_segment_size 0
		.amdhsa_uses_dynamic_stack 0
		.amdhsa_enable_private_segment 0
		.amdhsa_system_sgpr_workgroup_id_x 1
		.amdhsa_system_sgpr_workgroup_id_y 0
		.amdhsa_system_sgpr_workgroup_id_z 0
		.amdhsa_system_sgpr_workgroup_info 0
		.amdhsa_system_vgpr_workitem_id 2
		.amdhsa_next_free_vgpr 256
		.amdhsa_next_free_sgpr 102
		.amdhsa_accum_offset 256
		.amdhsa_reserve_vcc 1
		.amdhsa_float_round_mode_32 0
		.amdhsa_float_round_mode_16_64 0
		.amdhsa_float_denorm_mode_32 3
		.amdhsa_float_denorm_mode_16_64 3
		.amdhsa_dx10_clamp 1
		.amdhsa_ieee_mode 1
		.amdhsa_fp16_overflow 0
		.amdhsa_tg_split 0
		.amdhsa_exception_fp_ieee_invalid_op 0
		.amdhsa_exception_fp_denorm_src 0
		.amdhsa_exception_fp_ieee_div_zero 0
		.amdhsa_exception_fp_ieee_overflow 0
		.amdhsa_exception_fp_ieee_underflow 0
		.amdhsa_exception_fp_ieee_inexact 0
		.amdhsa_exception_int_div_zero 0
	.end_amdhsa_kernel

amdhsa.kernels:
  - .agpr_count:     0
    .args:
      - .offset:         0
        .size:           208
        .value_kind:     by_value
      - .offset:         208
        .size:           4
        .value_kind:     hidden_block_count_x
      - .offset:         212
        .size:           4
        .value_kind:     hidden_block_count_y
      - .offset:         216
        .size:           4
        .value_kind:     hidden_block_count_z
      - .offset:         220
        .size:           2
        .value_kind:     hidden_group_size_x
      - .offset:         222
        .size:           2
        .value_kind:     hidden_group_size_y
      - .offset:         224
        .size:           2
        .value_kind:     hidden_group_size_z
      - .offset:         226
        .size:           2
        .value_kind:     hidden_remainder_x
      - .offset:         228
        .size:           2
        .value_kind:     hidden_remainder_y
      - .offset:         230
        .size:           2
        .value_kind:     hidden_remainder_z
      - .offset:         248
        .size:           8
        .value_kind:     hidden_global_offset_x
      - .offset:         256
        .size:           8
        .value_kind:     hidden_global_offset_y
      - .offset:         264
        .size:           8
        .value_kind:     hidden_global_offset_z
      - .offset:         272
        .size:           2
        .value_kind:     hidden_grid_dims
      - .offset:         296
        .size:           8
        .value_kind:     hidden_multigrid_sync_arg
      - .offset:         328
        .size:           4
        .value_kind:     hidden_dynamic_lds_size
    .group_segment_fixed_size: 0
    .kernarg_segment_align: 8
    .kernarg_segment_size: 464
    .language:       OpenCL C
    .language_version:
      - 2
      - 0
    .max_flat_workgroup_size: 512
    .name:           _Z8yoco_fwd6Params
    .private_segment_fixed_size: 0
    .sgpr_count:     108
    .sgpr_spill_count: 192
    .symbol:         _Z8yoco_fwd6Params.kd
    .uniform_work_group_size: 1
    .uses_dynamic_stack: false
    .vgpr_count:     256
    .vgpr_spill_count: 0
    .wavefront_size: 64
